# GLA pass A and pass B: row addresses by running +-5120-byte step instead of a 64-bit multiply-add per load
# speedup vs baseline: 1.0042x; 1.0042x over previous
.LBB0_602:
	s_add_i32 s98, s76, s10
	s_lshl_b32 s98, s98, 1
	s_lshl_b32 s99, s10, 1
	s_add_i32 s99, s6, s99
	s_and_b64 vcc, s[24:25], exec
	s_cselect_b32 s98, s98, s99
	s_or_b32 s98, s98, s14
	s_lshl_b32 s98, s98, 14
	v_lshlrev_b32_e32 v196, 5, v202
	s_add_u32 s98, s98, 0x4f28000
	s_add_u32 s98, s100, s98
	s_addc_u32 s99, s101, 0
	global_load_dwordx4 v[228:231], v196, s[98:99]
	global_load_dwordx4 v[232:235], v196, s[98:99] offset:16
	v_cndmask_b32_e64 v0, v94, v85, s[74:75]
	v_cndmask_b32_e64 v4, v95, v84, s[74:75]
	v_sub_u32_e32 v4, v4, v0
	v_add_u32_e32 v0, s18, v0
	v_mul_i32_i24_e32 v4, 0x1400, v4
	v_mad_i64_i32 v[2:3], s[20:21], v0, s88, v[22:23]
	v_ashrrev_i32_e32 v5, 31, v4
	global_load_ushort v157, v[2:3], off
	global_load_ushort v156, v[2:3], off offset:512
	v_lshl_add_u64 v[2:3], v[2:3], 0, v[4:5]
	global_load_ushort v155, v[2:3], off
	global_load_ushort v154, v[2:3], off offset:512
	v_lshl_add_u64 v[2:3], v[2:3], 0, v[4:5]
	global_load_ushort v153, v[2:3], off
	global_load_ushort v152, v[2:3], off offset:512
	v_lshl_add_u64 v[2:3], v[2:3], 0, v[4:5]
	global_load_ushort v151, v[2:3], off
	global_load_ushort v150, v[2:3], off offset:512
	v_lshl_add_u64 v[2:3], v[2:3], 0, v[4:5]
	global_load_ushort v149, v[2:3], off
	global_load_ushort v148, v[2:3], off offset:512
	v_lshl_add_u64 v[2:3], v[2:3], 0, v[4:5]
	global_load_ushort v147, v[2:3], off
	global_load_ushort v146, v[2:3], off offset:512
	v_lshl_add_u64 v[2:3], v[2:3], 0, v[4:5]
	global_load_ushort v145, v[2:3], off
	global_load_ushort v144, v[2:3], off offset:512
	v_lshl_add_u64 v[2:3], v[2:3], 0, v[4:5]
	global_load_ushort v143, v[2:3], off
	global_load_ushort v142, v[2:3], off offset:512
	v_mov_b32_e32 v0, v202
	s_andn2_b64 vcc, exec, s[86:87]
	v_ashrrev_i32_e32 v6, 3, v0
	v_and_b32_e32 v11, -16, v6
	v_and_b32_e32 v10, 0x7f, v0
	v_sub_u32_e32 v0, 63, v11
	v_cndmask_b32_e64 v0, v0, v11, s[74:75]
	v_add_u32_e32 v0, s18, v0
	v_mov_b64_e32 v[2:3], s[94:95]
	s_nop 0
	v_mad_i64_i32 v[2:3], s[20:21], v0, s88, v[2:3]
	v_lshlrev_b32_e32 v0, 1, v10
	s_nop 0
	v_lshl_add_u64 v[2:3], v[2:3], 0, v[0:1]
	global_load_ushort v8, v[2:3], off offset:1024
	v_lshl_add_u64 v[2:3], v[2:3], 0, v[4:5]
	global_load_ushort v7, v[2:3], off offset:1024
	v_lshl_add_u64 v[2:3], v[2:3], 0, v[4:5]
	global_load_ushort v12, v[2:3], off offset:1024
	v_lshl_add_u64 v[2:3], v[2:3], 0, v[4:5]
	global_load_ushort v9, v[2:3], off offset:1024
	v_lshl_add_u64 v[2:3], v[2:3], 0, v[4:5]
	global_load_ushort v14, v[2:3], off offset:1024
	v_lshl_add_u64 v[2:3], v[2:3], 0, v[4:5]
	global_load_ushort v13, v[2:3], off offset:1024
	v_lshl_add_u64 v[2:3], v[2:3], 0, v[4:5]
	global_load_ushort v16, v[2:3], off offset:1024
	v_lshl_add_u64 v[2:3], v[2:3], 0, v[4:5]
	global_load_ushort v15, v[2:3], off offset:1024
	v_lshl_add_u64 v[2:3], v[2:3], 0, v[4:5]
	global_load_ushort v60, v[2:3], off offset:1024
	v_lshl_add_u64 v[2:3], v[2:3], 0, v[4:5]
	global_load_ushort v17, v[2:3], off offset:1024
	v_lshl_add_u64 v[2:3], v[2:3], 0, v[4:5]
	global_load_ushort v158, v[2:3], off offset:1024
	v_lshl_add_u64 v[2:3], v[2:3], 0, v[4:5]
	global_load_ushort v61, v[2:3], off offset:1024
	v_lshl_add_u64 v[2:3], v[2:3], 0, v[4:5]
	global_load_ushort v160, v[2:3], off offset:1024
	v_lshl_add_u64 v[2:3], v[2:3], 0, v[4:5]
	global_load_ushort v159, v[2:3], off offset:1024
	v_lshl_add_u64 v[2:3], v[2:3], 0, v[4:5]
	global_load_ushort v161, v[2:3], off offset:1024
	v_lshl_add_u64 v[2:3], v[2:3], 0, v[4:5]
	global_load_ushort v0, v[2:3], off offset:1024
	v_or_b32_e32 v6, 15, v6
	s_waitcnt vmcnt(12)
	v_lshl_or_b32 v3, v9, 16, v12
	v_lshl_or_b32 v2, v7, 16, v8
	s_waitcnt vmcnt(10)
	v_lshl_or_b32 v4, v13, 16, v14
	s_waitcnt vmcnt(8)
	v_lshl_or_b32 v5, v15, 16, v16
	s_waitcnt vmcnt(6)
	v_lshl_or_b32 v6, v17, 16, v60
	s_waitcnt vmcnt(4)
	v_lshl_or_b32 v7, v61, 16, v158
	s_waitcnt vmcnt(2)
	v_lshl_or_b32 v8, v159, 16, v160
	s_waitcnt vmcnt(0)
	v_lshl_or_b32 v9, v0, 16, v161
	v_mul_u32_u24_e32 v0, 0x90, v10
	v_lshlrev_b32_e32 v10, 1, v11
	v_add3_u32 v0, 0, v0, v10
	ds_write_b128 v0, v[2:5] offset:61440
	ds_write_b128 v0, v[6:9] offset:61456
	s_cbranch_vccnz .LBB0_604
	s_and_b64 s[20:21], s[74:75], exec
	s_cselect_b32 s4, 16, 24
	s_add_u32 s20, s8, s4
	s_addc_u32 s21, s9, 0
	s_load_dwordx2 s[20:21], s[20:21], 0x0
	s_waitcnt lgkmcnt(0)
	s_add_u32 s4, s20, s82
	s_addc_u32 s5, s21, s83
	s_add_u32 s20, s4, s91
	s_addc_u32 s21, s5, 0
	v_lshl_add_u64 v[10:11], v[24:25], 2, s[20:21]
	v_add_co_u32_e32 v60, vcc, 0x1000, v10
	global_load_dword v2, v[10:11], off
	global_load_dword v3, v[10:11], off offset:512
	global_load_dword v4, v[10:11], off offset:1024
	global_load_dword v5, v[10:11], off offset:1536
	global_load_dword v6, v[10:11], off offset:2048
	global_load_dword v7, v[10:11], off offset:2560
	global_load_dword v8, v[10:11], off offset:3072
	global_load_dword v9, v[10:11], off offset:3584
	v_addc_co_u32_e32 v61, vcc, 0, v11, vcc
	global_load_dword v10, v[60:61], off
	global_load_dword v11, v[60:61], off offset:512
	global_load_dword v12, v[60:61], off offset:1024
	global_load_dword v13, v[60:61], off offset:1536
	global_load_dword v14, v[60:61], off offset:2048
	global_load_dword v15, v[60:61], off offset:2560
	global_load_dword v16, v[60:61], off offset:3072
	global_load_dword v17, v[60:61], off offset:3584
	s_and_b64 s[20:21], s[74:75], exec
	s_cselect_b32 s15, s10, s11
	s_cmp_lt_i32 s15, 1
	s_cbranch_scc0 .LBB0_605
	s_branch .LBB0_610

.LBB0_665:
	s_or_b64 exec, exec, s[14:15]
	v_mov_b32_e32 v0, s69
	s_waitcnt vmcnt(0) lgkmcnt(0)
	s_barrier
	ds_read_b32 v0, v0
	s_movk_i32 s4, 0x36f
	s_mov_b64 s[14:15], -1
	s_waitcnt lgkmcnt(0)
	s_barrier
	v_cmp_lt_i32_e32 vcc, s4, v0
	v_readfirstlane_b32 s3, v0
	s_cbranch_vccnz .LBB0_660
	s_cmpk_gt_i32 s3, 0x6f
	s_cbranch_scc0 .LBB0_678
	s_add_i32 s4, s3, 0xfffffd90
	s_add_i32 s30, s3, 0xffffff90
	s_lshr_b32 s4, s4, 7
	s_add_i32 s4, s4, 16
	s_lshr_b32 s5, s30, 5
	s_cmpk_lt_u32 s30, 0x200
	s_cselect_b32 s6, 3, 5
	s_cselect_b32 s4, s5, s4
	s_cselect_b32 s7, 3, 15
	s_lshr_b32 s5, s30, s6
	s_lshr_b32 s6, s30, 1
	s_lshl_b32 s11, s4, 10
	s_and_b32 s6, s7, s6
	s_and_b32 s5, s5, 3
	s_and_b32 s10, s3, 1
	s_lshl_b32 s7, s4, 8
	s_addk_i32 s11, 0xd000
	s_cmp_lt_u32 s4, 16
	s_cselect_b32 s4, s7, s11
	s_lshl_b32 s6, s6, 6
	s_add_i32 s7, s4, s6
	s_cmp_eq_u32 s10, 0
	v_mov_b32_e32 v18, v202
	s_cselect_b64 vcc, -1, 0
	s_lshl_b32 s6, s5, 6
	s_lshl_b32 s4, s5, 7
	s_add_u32 s14, s74, s4
	v_and_b32_e32 v15, 63, v18
	v_ashrrev_i32_e32 v14, 6, v18
	v_lshlrev_b32_e32 v6, 3, v14
	s_addc_u32 s15, s75, 0
	v_lshlrev_b32_e32 v0, 1, v15
	v_lshl_add_u64 v[2:3], s[14:15], 0, v[0:1]
	s_movk_i32 s96, 0x1400
	s_cmp_eq_u32 s10, 0
	s_cselect_b32 s96, s96, 0xffffec00
	s_ashr_i32 s97, s96, 31
	v_sub_u32_e32 v0, 63, v6
	v_cndmask_b32_e32 v0, v0, v6, vcc
	v_add_u32_e32 v0, s7, v0
	v_mad_i64_i32 v[4:5], s[14:15], v0, s88, v[2:3]
	global_load_ushort v16, v[4:5], off offset:512
	v_lshl_add_u64 v[4:5], v[4:5], 0, s[96:97]
	global_load_ushort v21, v[4:5], off offset:512
	v_lshl_add_u64 v[4:5], v[4:5], 0, s[96:97]
	global_load_ushort v17, v[4:5], off offset:512
	v_lshl_add_u64 v[4:5], v[4:5], 0, s[96:97]
	global_load_ushort v22, v[4:5], off offset:512
	v_lshl_add_u64 v[4:5], v[4:5], 0, s[96:97]
	global_load_ushort v19, v[4:5], off offset:512
	v_lshl_add_u64 v[4:5], v[4:5], 0, s[96:97]
	global_load_ushort v23, v[4:5], off offset:512
	v_lshl_add_u64 v[4:5], v[4:5], 0, s[96:97]
	global_load_ushort v20, v[4:5], off offset:512
	v_lshl_add_u64 v[4:5], v[4:5], 0, s[96:97]
	global_load_ushort v24, v[4:5], off offset:512
	v_mov_b32_e32 v0, v202
	s_lshl_b32 s24, s5, 8
	v_ashrrev_i32_e32 v6, 3, v0
	v_and_b32_e32 v11, -16, v6
	v_and_b32_e32 v10, 0x7f, v0
	v_sub_u32_e32 v0, 63, v11
	v_cndmask_b32_e32 v0, v0, v11, vcc
	v_add_u32_e32 v0, s7, v0
	v_mov_b64_e32 v[2:3], s[74:75]
	s_mov_b32 s25, s31
	v_mad_i64_i32 v[4:5], s[14:15], v0, s88, v[2:3]
	v_lshlrev_b32_e32 v0, 1, v10
	v_lshl_add_u64 v[4:5], v[4:5], 0, s[24:25]
	s_nop 0
	v_lshl_add_u64 v[4:5], v[4:5], 0, v[0:1]
	global_load_ushort v8, v[4:5], off offset:1024
	v_lshl_add_u64 v[4:5], v[4:5], 0, s[96:97]
	global_load_ushort v7, v[4:5], off offset:1024
	v_lshl_add_u64 v[4:5], v[4:5], 0, s[96:97]
	global_load_ushort v12, v[4:5], off offset:1024
	v_lshl_add_u64 v[4:5], v[4:5], 0, s[96:97]
	global_load_ushort v9, v[4:5], off offset:1024
	v_lshl_add_u64 v[4:5], v[4:5], 0, s[96:97]
	global_load_ushort v25, v[4:5], off offset:1024
	v_lshl_add_u64 v[4:5], v[4:5], 0, s[96:97]
	global_load_ushort v13, v[4:5], off offset:1024
	v_lshl_add_u64 v[4:5], v[4:5], 0, s[96:97]
	global_load_ushort v27, v[4:5], off offset:1024
	v_lshl_add_u64 v[4:5], v[4:5], 0, s[96:97]
	global_load_ushort v26, v[4:5], off offset:1024
	v_lshl_add_u64 v[4:5], v[4:5], 0, s[96:97]
	global_load_ushort v29, v[4:5], off offset:1024
	v_lshl_add_u64 v[4:5], v[4:5], 0, s[96:97]
	global_load_ushort v28, v[4:5], off offset:1024
	v_lshl_add_u64 v[4:5], v[4:5], 0, s[96:97]
	global_load_ushort v31, v[4:5], off offset:1024
	v_lshl_add_u64 v[4:5], v[4:5], 0, s[96:97]
	global_load_ushort v30, v[4:5], off offset:1024
	v_lshl_add_u64 v[4:5], v[4:5], 0, s[96:97]
	global_load_ushort v33, v[4:5], off offset:1024
	v_lshl_add_u64 v[4:5], v[4:5], 0, s[96:97]
	global_load_ushort v32, v[4:5], off offset:1024
	v_lshl_add_u64 v[4:5], v[4:5], 0, s[96:97]
	global_load_ushort v34, v[4:5], off offset:1024
	v_lshl_add_u64 v[4:5], v[4:5], 0, s[96:97]
	global_load_ushort v0, v[4:5], off offset:1024
	v_or_b32_e32 v6, 15, v6
	v_readlane_b32 s96, v253, 54
	v_readlane_b32 s97, v253, 55
	s_lshl_b32 s98, s10, 6
	s_add_u32 s96, s96, s98
	s_addc_u32 s97, s97, 0
	v_and_b32_e32 v150, 15, v202
	v_lshlrev_b32_e32 v150, 2, v150
	v_mov_b32_e32 v151, 0
	v_ashrrev_i32_e32 v152, 4, v202
	v_lshl_add_u64 v[150:151], s[96:97], 0, v[150:151]
	v_add_u32_e32 v153, 32, v152
	v_sub_u32_e32 v154, 63, v152
	v_sub_u32_e32 v155, 63, v153
	v_cndmask_b32_e32 v152, v154, v152, vcc
	v_cndmask_b32_e32 v153, v155, v153, vcc
	v_add_u32_e32 v152, s7, v152
	v_add_u32_e32 v153, s7, v153
	v_lshlrev_b32_e32 v156, 7, v152
	v_mov_b32_e32 v157, 0
	v_lshlrev_b32_e32 v158, 7, v153
	v_mov_b32_e32 v159, 0
	v_lshl_add_u64 v[156:157], v[150:151], 0, v[156:157]
	v_lshl_add_u64 v[158:159], v[150:151], 0, v[158:159]
	s_cmp_eq_u32 s10, 0
	s_movk_i32 s98, 0x68
	s_cselect_b32 s98, s98, 0x78
	global_load_dword v130, v[156:157], off
	global_load_dword v131, v[158:159], off
	s_add_u32 s96, s8, s98
	s_addc_u32 s97, s9, 0
	s_load_dwordx2 s[96:97], s[96:97], 0x0
	s_add_u32 s98, s8, s98
	s_addc_u32 s99, s9, 0
	s_load_dwordx2 s[98:99], s[98:99], 0x8
	v_and_b32_e32 v160, 63, v202
	v_mov_b32_e32 v162, s6
	v_lshlrev_b32_e32 v161, 2, v160
	v_mov_b32_e32 v163, 0
	v_lshl_add_u32 v162, v162, 2, v161
	v_mov_b32_e32 v164, 0x1000
	v_mov_b32_e32 v165, 0
	s_waitcnt lgkmcnt(0)
	s_add_u32 s96, s96, s22
	s_addc_u32 s97, s97, s23
	v_lshl_add_u64 v[162:163], s[96:97], 0, v[162:163]
	s_nop 0
	v_lshl_add_u64 v[166:167], v[162:163], 0, v[164:165]
	global_load_dword v132, v[162:163], off
	global_load_dword v133, v[162:163], off offset:1024
	global_load_dword v134, v[162:163], off offset:2048
	global_load_dword v135, v[162:163], off offset:3072
	v_lshl_add_u64 v[162:163], v[166:167], 0, v[164:165]
	global_load_dword v136, v[166:167], off
	global_load_dword v137, v[166:167], off offset:1024
	global_load_dword v138, v[166:167], off offset:2048
	global_load_dword v139, v[166:167], off offset:3072
	v_lshl_add_u64 v[166:167], v[162:163], 0, v[164:165]
	global_load_dword v140, v[162:163], off
	global_load_dword v141, v[162:163], off offset:1024
	global_load_dword v142, v[162:163], off offset:2048
	global_load_dword v143, v[162:163], off offset:3072
	v_readlane_b32 s96, v254, 41
	global_load_dword v144, v[166:167], off
	global_load_dword v145, v[166:167], off offset:1024
	global_load_dword v146, v[166:167], off offset:2048
	global_load_dword v147, v[166:167], off offset:3072
	s_or_b32 s96, s6, s96
	v_mov_b32_e32 v169, 0
	v_or_b32_e32 v168, s96, v160
	s_nop 0
	v_lshl_add_u64 v[168:169], v[168:169], 2, s[98:99]
	s_nop 0
	global_load_dword v148, v[168:169], off
	s_waitcnt vmcnt(31)
	v_lshl_or_b32 v3, v9, 16, v12
	v_lshl_or_b32 v2, v7, 16, v8
	s_waitcnt vmcnt(29)
	v_lshl_or_b32 v4, v13, 16, v25
	s_movk_i32 s4, 0x400
	s_waitcnt vmcnt(27)
	v_lshl_or_b32 v5, v26, 16, v27
	s_waitcnt vmcnt(25)
	v_lshl_or_b32 v6, v28, 16, v29
	s_waitcnt vmcnt(23)
	v_lshl_or_b32 v7, v30, 16, v31
	s_waitcnt vmcnt(21)
	v_lshl_or_b32 v8, v32, 16, v33
	s_waitcnt vmcnt(19)
	v_lshl_or_b32 v9, v0, 16, v34
	v_mul_u32_u24_e32 v0, 0x90, v10
	v_lshlrev_b32_e32 v10, 1, v11
	v_add3_u32 v0, 0, v0, v10
	ds_write_b128 v0, v[2:5] offset:9216
	ds_write_b128 v0, v[6:9] offset:9232
	v_mov_b32_e32 v2, v202
	s_nop 0
	s_waitcnt vmcnt(17)
	s_movk_i32 s4, 0x6c00
	v_lshl_add_u32 v9, v2, 2, s4
	ds_write2st64_b32 v9, v130, v131 offset1:8
